# barrier leader no longer waits for its own L1 invalidate before releasing the others (counted wait on the arrival atomic only)
# baseline (speedup 1.0000x reference)
; __device__ __forceinline__ unsigned xb_ld(unsigned* p)              { return __hip_atomic_load(p, __ATOMIC_RELAXED, __HIP_MEMORY_SCOPE_AGENT); }
; __device__ __forceinline__ unsigned xb_add(unsigned* p, unsigned v) { return __hip_atomic_fetch_add(p, v, __ATOMIC_RELAXED, __HIP_MEMORY_SCOPE_AGENT); }
; #define XB_SPIN(cond, bar) do { unsigned _sp = 0; while (cond) { __builtin_amdgcn_s_sleep(1); \
;     if ((++_sp & 255u) == 0u) { if (xb_ld(&(bar)[XB_TMO])) break; if (_sp > XB_SPIN_CAP) { atomicAdd(&(bar)[XB_TMO], 1u); break; } } } } while (0)
; __device__ __forceinline__ void xcd_barrier(const XcdBarrier& b, bool tid0) {
;     ...
;         unsigned nloc = b.st[0], nx = b.st[1];
;         if (nloc == 0u) { xcd_barrier_complete(bar, b.x, b.G, nloc, nx); b.st[0] = nloc; b.st[1] = nx; }
;         const unsigned old = xb_add(&bar[XB_XSUB(b.x)], 1u);
;         const unsigned gen = old / nloc;
;         if (old + 1u == (gen + 1u) * nloc) {
;             __builtin_amdgcn_fence(__ATOMIC_RELEASE, "agent");
;             asm volatile("s_waitcnt vmcnt(0)" ::: "memory");
;             const unsigned og = xb_add(&bar[XB_TOP], 1u);
;             const unsigned tg = og / nx;
;             if (og + 1u == (tg + 1u) * nx) xb_add(&bar[XB_TOPGEN], 1u);
;             else XB_SPIN(xb_ld(&bar[XB_TOPGEN]) == tg, bar);
;             __builtin_amdgcn_fence(__ATOMIC_ACQUIRE, "agent");
;             xb_add(&bar[XB_XGEN(b.x)], 1u);
;             asm volatile("s_waitcnt vmcnt(0)" ::: "memory");
;         } else {
;             XB_SPIN(xb_ld(&bar[XB_XGEN(b.x)]) == gen, bar);
.LBB0_189:
	s_or_b64 exec, exec, s[8:9]
	v_cvt_f32_u32_e32 v4, v2
	s_waitcnt vmcnt(1)
	v_readfirstlane_b32 s0, v3
	v_sub_u32_e32 v3, 0, v2
	v_rcp_iflag_f32_e32 v4, v4
	v_add_u32_e32 v5, s0, v1
	v_mul_f32_e32 v4, 0x4f7ffffe, v4
	v_cvt_u32_f32_e32 v4, v4
	v_mul_lo_u32 v1, v3, v4
	v_mul_hi_u32 v1, v4, v1
	v_add_u32_e32 v1, v4, v1
	v_mul_hi_u32 v1, v5, v1
	v_mul_lo_u32 v3, v1, v2
	v_sub_u32_e32 v3, v5, v3
	v_add_u32_e32 v4, 1, v1
	v_cmp_ge_u32_e32 vcc, v3, v2
	s_nop 1
	v_cndmask_b32_e32 v1, v1, v4, vcc
	v_sub_u32_e32 v4, v3, v2
	v_cndmask_b32_e32 v3, v3, v4, vcc
	v_add_u32_e32 v4, 1, v1
	v_cmp_ge_u32_e32 vcc, v3, v2
	v_add_u32_e32 v3, 1, v5
	s_nop 0
	v_cndmask_b32_e32 v1, v1, v4, vcc
	v_mul_lo_u32 v4, v2, v1
	v_add_u32_e32 v2, v4, v2
	v_cmp_ne_u32_e32 vcc, v3, v2
	s_and_saveexec_b64 s[0:1], vcc
	s_xor_b64 s[8:9], exec, s[0:1]
	s_cbranch_execz .LBB0_203
	s_waitcnt lgkmcnt(0)
	global_load_dword v0, v254, s[6:7] offset:1024 sc1
	s_add_u32 s14, s6, 0x2400
	s_addc_u32 s15, s7, 0
	s_waitcnt vmcnt(0)
	v_cmp_eq_u32_e32 vcc, v0, v1
	s_and_saveexec_b64 s[10:11], vcc
	s_cbranch_execz .LBB0_202
	s_add_u32 s12, s4, 0x26120200
	s_addc_u32 s13, s5, 0
	s_mov_b32 s21, 1
	s_mov_b64 s[24:25], 0
	s_branch .LBB0_193

; __device__ __forceinline__ unsigned xb_ld(unsigned* p)              { return __hip_atomic_load(p, __ATOMIC_RELAXED, __HIP_MEMORY_SCOPE_AGENT); }
; __device__ __forceinline__ unsigned xb_add(unsigned* p, unsigned v) { return __hip_atomic_fetch_add(p, v, __ATOMIC_RELAXED, __HIP_MEMORY_SCOPE_AGENT); }
; #define XB_SPIN(cond, bar) do { unsigned _sp = 0; while (cond) { __builtin_amdgcn_s_sleep(1); \
;     if ((++_sp & 255u) == 0u) { if (xb_ld(&(bar)[XB_TMO])) break; if (_sp > XB_SPIN_CAP) { atomicAdd(&(bar)[XB_TMO], 1u); break; } } } } while (0)
; __device__ __forceinline__ void xcd_barrier(const XcdBarrier& b, bool tid0) {
;     ...
;         unsigned nloc = b.st[0], nx = b.st[1];
;         if (nloc == 0u) { xcd_barrier_complete(bar, b.x, b.G, nloc, nx); b.st[0] = nloc; b.st[1] = nx; }
;         const unsigned old = xb_add(&bar[XB_XSUB(b.x)], 1u);
;         const unsigned gen = old / nloc;
;         if (old + 1u == (gen + 1u) * nloc) {
;             __builtin_amdgcn_fence(__ATOMIC_RELEASE, "agent");
;             asm volatile("s_waitcnt vmcnt(0)" ::: "memory");
;             const unsigned og = xb_add(&bar[XB_TOP], 1u);
;             const unsigned tg = og / nx;
;             if (og + 1u == (tg + 1u) * nx) xb_add(&bar[XB_TOPGEN], 1u);
;             else XB_SPIN(xb_ld(&bar[XB_TOPGEN]) == tg, bar);
;             __builtin_amdgcn_fence(__ATOMIC_ACQUIRE, "agent");
;             xb_add(&bar[XB_XGEN(b.x)], 1u);
;             asm volatile("s_waitcnt vmcnt(0)" ::: "memory");
;         } else {
;             XB_SPIN(xb_ld(&bar[XB_XGEN(b.x)]) == gen, bar);
.LBB0_261:
	s_or_b64 exec, exec, s[8:9]
	v_cvt_f32_u32_e32 v4, v2
	s_waitcnt vmcnt(1)
	v_readfirstlane_b32 s0, v3
	v_sub_u32_e32 v3, 0, v2
	v_rcp_iflag_f32_e32 v4, v4
	v_add_u32_e32 v5, s0, v1
	v_mul_f32_e32 v4, 0x4f7ffffe, v4
	v_cvt_u32_f32_e32 v4, v4
	v_mul_lo_u32 v1, v3, v4
	v_mul_hi_u32 v1, v4, v1
	v_add_u32_e32 v1, v4, v1
	v_mul_hi_u32 v1, v5, v1
	v_mul_lo_u32 v3, v1, v2
	v_sub_u32_e32 v3, v5, v3
	v_add_u32_e32 v4, 1, v1
	v_cmp_ge_u32_e32 vcc, v3, v2
	s_nop 1
	v_cndmask_b32_e32 v1, v1, v4, vcc
	v_sub_u32_e32 v4, v3, v2
	v_cndmask_b32_e32 v3, v3, v4, vcc
	v_add_u32_e32 v4, 1, v1
	v_cmp_ge_u32_e32 vcc, v3, v2
	v_add_u32_e32 v3, 1, v5
	s_nop 0
	v_cndmask_b32_e32 v1, v1, v4, vcc
	v_mul_lo_u32 v4, v2, v1
	v_add_u32_e32 v2, v4, v2
	v_cmp_ne_u32_e32 vcc, v3, v2
	s_and_saveexec_b64 s[0:1], vcc
	s_xor_b64 s[8:9], exec, s[0:1]
	s_cbranch_execz .LBB0_275
	s_waitcnt lgkmcnt(0)
	global_load_dword v0, v254, s[6:7] offset:1024 sc1
	s_add_u32 s12, s6, 0x2400
	s_addc_u32 s13, s7, 0
	s_waitcnt vmcnt(0)
	v_cmp_eq_u32_e32 vcc, v0, v1
	s_and_saveexec_b64 s[10:11], vcc
	s_cbranch_execz .LBB0_274
	s_mov_b32 s19, 1
	s_mov_b64 s[14:15], 0
	s_branch .LBB0_265

; __device__ __forceinline__ unsigned xb_ld(unsigned* p)              { return __hip_atomic_load(p, __ATOMIC_RELAXED, __HIP_MEMORY_SCOPE_AGENT); }
; __device__ __forceinline__ unsigned xb_add(unsigned* p, unsigned v) { return __hip_atomic_fetch_add(p, v, __ATOMIC_RELAXED, __HIP_MEMORY_SCOPE_AGENT); }
; #define XB_SPIN(cond, bar) do { unsigned _sp = 0; while (cond) { __builtin_amdgcn_s_sleep(1); \
;     if ((++_sp & 255u) == 0u) { if (xb_ld(&(bar)[XB_TMO])) break; if (_sp > XB_SPIN_CAP) { atomicAdd(&(bar)[XB_TMO], 1u); break; } } } } while (0)
; __device__ __forceinline__ void xcd_barrier(const XcdBarrier& b, bool tid0) {
;     ...
;             const unsigned og = xb_add(&bar[XB_TOP], 1u);
;             const unsigned tg = og / nx;
;             if (og + 1u == (tg + 1u) * nx) xb_add(&bar[XB_TOPGEN], 1u);
;             else XB_SPIN(xb_ld(&bar[XB_TOPGEN]) == tg, bar);
;             __builtin_amdgcn_fence(__ATOMIC_ACQUIRE, "agent");
;             xb_add(&bar[XB_XGEN(b.x)], 1u);
;             asm volatile("s_waitcnt vmcnt(0)" ::: "memory");
.LBB0_290:
	s_or_b64 exec, exec, s[10:11]
	s_and_saveexec_b64 s[4:5], s[0:1]
	s_cbranch_execz .LBB0_292
	global_atomic_add v[0:1], v234, off
.LBB0_292:
	s_or_b64 exec, exec, s[4:5]
	s_waitcnt vmcnt(0)
.Lfastbar_0:
	s_mov_b64 s[0:1], exec
	v_mbcnt_lo_u32_b32 v0, s0, 0
	v_mbcnt_hi_u32_b32 v0, s1, v0
	v_cmp_eq_u32_e32 vcc, 0, v0
	s_and_saveexec_b64 s[4:5], vcc
	s_cbranch_execz .LBB0_294
	s_bcnt1_i32_b64 s0, s[0:1]
	v_mov_b32_e32 v0, s0
	global_atomic_add v254, v0, s[6:7] offset:1024

; __device__ __forceinline__ unsigned xb_ld(unsigned* p)              { return __hip_atomic_load(p, __ATOMIC_RELAXED, __HIP_MEMORY_SCOPE_AGENT); }
; __device__ __forceinline__ unsigned xb_add(unsigned* p, unsigned v) { return __hip_atomic_fetch_add(p, v, __ATOMIC_RELAXED, __HIP_MEMORY_SCOPE_AGENT); }
; #define XB_SPIN(cond, bar) do { unsigned _sp = 0; while (cond) { __builtin_amdgcn_s_sleep(1); \
;     if ((++_sp & 255u) == 0u) { if (xb_ld(&(bar)[XB_TMO])) break; if (_sp > XB_SPIN_CAP) { atomicAdd(&(bar)[XB_TMO], 1u); break; } } } } while (0)
; __device__ __forceinline__ void xcd_barrier(const XcdBarrier& b, bool tid0) {
;     ...
;         unsigned nloc = b.st[0], nx = b.st[1];
;         if (nloc == 0u) { xcd_barrier_complete(bar, b.x, b.G, nloc, nx); b.st[0] = nloc; b.st[1] = nx; }
;         const unsigned old = xb_add(&bar[XB_XSUB(b.x)], 1u);
;         const unsigned gen = old / nloc;
;         if (old + 1u == (gen + 1u) * nloc) {
;             __builtin_amdgcn_fence(__ATOMIC_RELEASE, "agent");
;             asm volatile("s_waitcnt vmcnt(0)" ::: "memory");
;             const unsigned og = xb_add(&bar[XB_TOP], 1u);
;             const unsigned tg = og / nx;
;             if (og + 1u == (tg + 1u) * nx) xb_add(&bar[XB_TOPGEN], 1u);
;             else XB_SPIN(xb_ld(&bar[XB_TOPGEN]) == tg, bar);
;             __builtin_amdgcn_fence(__ATOMIC_ACQUIRE, "agent");
;             xb_add(&bar[XB_XGEN(b.x)], 1u);
;             asm volatile("s_waitcnt vmcnt(0)" ::: "memory");
;         } else {
;             XB_SPIN(xb_ld(&bar[XB_XGEN(b.x)]) == gen, bar);
.LBB0_384:
	s_or_b64 exec, exec, s[8:9]
	v_cvt_f32_u32_e32 v4, v2
	s_waitcnt vmcnt(1)
	v_readfirstlane_b32 s0, v3
	v_sub_u32_e32 v3, 0, v2
	v_rcp_iflag_f32_e32 v4, v4
	v_add_u32_e32 v5, s0, v1
	v_mul_f32_e32 v4, 0x4f7ffffe, v4
	v_cvt_u32_f32_e32 v4, v4
	v_mul_lo_u32 v1, v3, v4
	v_mul_hi_u32 v1, v4, v1
	v_add_u32_e32 v1, v4, v1
	v_mul_hi_u32 v1, v5, v1
	v_mul_lo_u32 v3, v1, v2
	v_sub_u32_e32 v3, v5, v3
	v_add_u32_e32 v4, 1, v1
	v_cmp_ge_u32_e32 vcc, v3, v2
	s_nop 1
	v_cndmask_b32_e32 v1, v1, v4, vcc
	v_sub_u32_e32 v4, v3, v2
	v_cndmask_b32_e32 v3, v3, v4, vcc
	v_add_u32_e32 v4, 1, v1
	v_cmp_ge_u32_e32 vcc, v3, v2
	v_add_u32_e32 v3, 1, v5
	s_nop 0
	v_cndmask_b32_e32 v1, v1, v4, vcc
	v_mul_lo_u32 v4, v2, v1
	v_add_u32_e32 v2, v4, v2
	v_cmp_ne_u32_e32 vcc, v3, v2
	s_and_saveexec_b64 s[0:1], vcc
	s_xor_b64 s[8:9], exec, s[0:1]
	s_cbranch_execz .LBB0_398
	s_waitcnt lgkmcnt(0)
	global_load_dword v0, v254, s[6:7] offset:1024 sc1
	s_add_u32 s14, s6, 0x2400
	s_addc_u32 s15, s7, 0
	s_waitcnt vmcnt(0)
	v_cmp_eq_u32_e32 vcc, v0, v1
	s_and_saveexec_b64 s[10:11], vcc
	s_cbranch_execz .LBB0_397
	s_add_u32 s12, s4, 0x26120200
	s_addc_u32 s13, s5, 0
	s_mov_b32 s21, 1
	s_mov_b64 s[26:27], 0
	s_branch .LBB0_388

; __device__ __forceinline__ unsigned xb_ld(unsigned* p)              { return __hip_atomic_load(p, __ATOMIC_RELAXED, __HIP_MEMORY_SCOPE_AGENT); }
; __device__ __forceinline__ unsigned xb_add(unsigned* p, unsigned v) { return __hip_atomic_fetch_add(p, v, __ATOMIC_RELAXED, __HIP_MEMORY_SCOPE_AGENT); }
; #define XB_SPIN(cond, bar) do { unsigned _sp = 0; while (cond) { __builtin_amdgcn_s_sleep(1); \
;     if ((++_sp & 255u) == 0u) { if (xb_ld(&(bar)[XB_TMO])) break; if (_sp > XB_SPIN_CAP) { atomicAdd(&(bar)[XB_TMO], 1u); break; } } } } while (0)
; __device__ __forceinline__ void xcd_barrier(const XcdBarrier& b, bool tid0) {
;     ...
;         unsigned nloc = b.st[0], nx = b.st[1];
;         if (nloc == 0u) { xcd_barrier_complete(bar, b.x, b.G, nloc, nx); b.st[0] = nloc; b.st[1] = nx; }
;         const unsigned old = xb_add(&bar[XB_XSUB(b.x)], 1u);
;         const unsigned gen = old / nloc;
;         if (old + 1u == (gen + 1u) * nloc) {
;             __builtin_amdgcn_fence(__ATOMIC_RELEASE, "agent");
;             asm volatile("s_waitcnt vmcnt(0)" ::: "memory");
;             const unsigned og = xb_add(&bar[XB_TOP], 1u);
;             const unsigned tg = og / nx;
;             if (og + 1u == (tg + 1u) * nx) xb_add(&bar[XB_TOPGEN], 1u);
;             else XB_SPIN(xb_ld(&bar[XB_TOPGEN]) == tg, bar);
;             __builtin_amdgcn_fence(__ATOMIC_ACQUIRE, "agent");
;             xb_add(&bar[XB_XGEN(b.x)], 1u);
;             asm volatile("s_waitcnt vmcnt(0)" ::: "memory");
;         } else {
;             XB_SPIN(xb_ld(&bar[XB_XGEN(b.x)]) == gen, bar);
.LBB0_557:
	s_or_b64 exec, exec, s[8:9]
	v_cvt_f32_u32_e32 v4, v2
	s_waitcnt vmcnt(1)
	v_readfirstlane_b32 s0, v3
	v_sub_u32_e32 v3, 0, v2
	v_rcp_iflag_f32_e32 v4, v4
	v_add_u32_e32 v5, s0, v1
	v_mul_f32_e32 v4, 0x4f7ffffe, v4
	v_cvt_u32_f32_e32 v4, v4
	v_mul_lo_u32 v1, v3, v4
	v_mul_hi_u32 v1, v4, v1
	v_add_u32_e32 v1, v4, v1
	v_mul_hi_u32 v1, v5, v1
	v_mul_lo_u32 v3, v1, v2
	v_sub_u32_e32 v3, v5, v3
	v_add_u32_e32 v4, 1, v1
	v_cmp_ge_u32_e32 vcc, v3, v2
	s_nop 1
	v_cndmask_b32_e32 v1, v1, v4, vcc
	v_sub_u32_e32 v4, v3, v2
	v_cndmask_b32_e32 v3, v3, v4, vcc
	v_add_u32_e32 v4, 1, v1
	v_cmp_ge_u32_e32 vcc, v3, v2
	v_add_u32_e32 v3, 1, v5
	s_nop 0
	v_cndmask_b32_e32 v1, v1, v4, vcc
	v_mul_lo_u32 v4, v2, v1
	v_add_u32_e32 v2, v4, v2
	v_cmp_ne_u32_e32 vcc, v3, v2
	s_and_saveexec_b64 s[0:1], vcc
	s_xor_b64 s[8:9], exec, s[0:1]
	s_cbranch_execz .LBB0_571
	s_waitcnt lgkmcnt(0)
	global_load_dword v0, v254, s[6:7] offset:1024 sc1
	s_add_u32 s12, s6, 0x2400
	s_addc_u32 s13, s7, 0
	s_waitcnt vmcnt(0)
	v_cmp_eq_u32_e32 vcc, v0, v1
	s_and_saveexec_b64 s[10:11], vcc
	s_cbranch_execz .LBB0_570
	s_mov_b32 s21, 1
	s_mov_b64 s[14:15], 0
	s_branch .LBB0_561

; __device__ __forceinline__ unsigned xb_ld(unsigned* p)              { return __hip_atomic_load(p, __ATOMIC_RELAXED, __HIP_MEMORY_SCOPE_AGENT); }
; __device__ __forceinline__ unsigned xb_add(unsigned* p, unsigned v) { return __hip_atomic_fetch_add(p, v, __ATOMIC_RELAXED, __HIP_MEMORY_SCOPE_AGENT); }
; #define XB_SPIN(cond, bar) do { unsigned _sp = 0; while (cond) { __builtin_amdgcn_s_sleep(1); \
;     if ((++_sp & 255u) == 0u) { if (xb_ld(&(bar)[XB_TMO])) break; if (_sp > XB_SPIN_CAP) { atomicAdd(&(bar)[XB_TMO], 1u); break; } } } } while (0)
; __device__ __forceinline__ void xcd_barrier(const XcdBarrier& b, bool tid0) {
;     ...
;             const unsigned og = xb_add(&bar[XB_TOP], 1u);
;             const unsigned tg = og / nx;
;             if (og + 1u == (tg + 1u) * nx) xb_add(&bar[XB_TOPGEN], 1u);
;             else XB_SPIN(xb_ld(&bar[XB_TOPGEN]) == tg, bar);
;             __builtin_amdgcn_fence(__ATOMIC_ACQUIRE, "agent");
;             xb_add(&bar[XB_XGEN(b.x)], 1u);
;             asm volatile("s_waitcnt vmcnt(0)" ::: "memory");
.LBB0_586:
	s_or_b64 exec, exec, s[10:11]
	s_and_saveexec_b64 s[4:5], s[0:1]
	s_cbranch_execz .LBB0_588
	global_atomic_add v[0:1], v234, off
.LBB0_588:
	s_or_b64 exec, exec, s[4:5]
	s_waitcnt vmcnt(0)

; __device__ __forceinline__ unsigned xb_ld(unsigned* p)              { return __hip_atomic_load(p, __ATOMIC_RELAXED, __HIP_MEMORY_SCOPE_AGENT); }
; __device__ __forceinline__ unsigned xb_add(unsigned* p, unsigned v) { return __hip_atomic_fetch_add(p, v, __ATOMIC_RELAXED, __HIP_MEMORY_SCOPE_AGENT); }
; #define XB_SPIN(cond, bar) do { unsigned _sp = 0; while (cond) { __builtin_amdgcn_s_sleep(1); \
;     if ((++_sp & 255u) == 0u) { if (xb_ld(&(bar)[XB_TMO])) break; if (_sp > XB_SPIN_CAP) { atomicAdd(&(bar)[XB_TMO], 1u); break; } } } } while (0)
; __device__ __forceinline__ void xcd_barrier(const XcdBarrier& b, bool tid0) {
;     ...
;             const unsigned og = xb_add(&bar[XB_TOP], 1u);
;             const unsigned tg = og / nx;
;             if (og + 1u == (tg + 1u) * nx) xb_add(&bar[XB_TOPGEN], 1u);
;             else XB_SPIN(xb_ld(&bar[XB_TOPGEN]) == tg, bar);
;             __builtin_amdgcn_fence(__ATOMIC_ACQUIRE, "agent");
;             xb_add(&bar[XB_XGEN(b.x)], 1u);
;             asm volatile("s_waitcnt vmcnt(0)" ::: "memory");
.LBB0_654:
	s_or_b64 exec, exec, s[10:11]
	s_and_saveexec_b64 s[4:5], s[0:1]
	s_cbranch_execz .LBB0_656
	global_atomic_add v[0:1], v234, off
.LBB0_656:
	s_or_b64 exec, exec, s[4:5]
	s_waitcnt vmcnt(0)

; __device__ __forceinline__ unsigned xb_ld(unsigned* p)              { return __hip_atomic_load(p, __ATOMIC_RELAXED, __HIP_MEMORY_SCOPE_AGENT); }
; __device__ __forceinline__ unsigned xb_add(unsigned* p, unsigned v) { return __hip_atomic_fetch_add(p, v, __ATOMIC_RELAXED, __HIP_MEMORY_SCOPE_AGENT); }
; #define XB_SPIN(cond, bar) do { unsigned _sp = 0; while (cond) { __builtin_amdgcn_s_sleep(1); \
;     if ((++_sp & 255u) == 0u) { if (xb_ld(&(bar)[XB_TMO])) break; if (_sp > XB_SPIN_CAP) { atomicAdd(&(bar)[XB_TMO], 1u); break; } } } } while (0)
; __device__ __forceinline__ void xcd_barrier(const XcdBarrier& b, bool tid0) {
;     ...
;         unsigned nloc = b.st[0], nx = b.st[1];
;         if (nloc == 0u) { xcd_barrier_complete(bar, b.x, b.G, nloc, nx); b.st[0] = nloc; b.st[1] = nx; }
;         const unsigned old = xb_add(&bar[XB_XSUB(b.x)], 1u);
;         const unsigned gen = old / nloc;
;         if (old + 1u == (gen + 1u) * nloc) {
;             __builtin_amdgcn_fence(__ATOMIC_RELEASE, "agent");
;             asm volatile("s_waitcnt vmcnt(0)" ::: "memory");
;             const unsigned og = xb_add(&bar[XB_TOP], 1u);
;             const unsigned tg = og / nx;
;             if (og + 1u == (tg + 1u) * nx) xb_add(&bar[XB_TOPGEN], 1u);
;             else XB_SPIN(xb_ld(&bar[XB_TOPGEN]) == tg, bar);
;             __builtin_amdgcn_fence(__ATOMIC_ACQUIRE, "agent");
;             xb_add(&bar[XB_XGEN(b.x)], 1u);
;             asm volatile("s_waitcnt vmcnt(0)" ::: "memory");
;         } else {
;             XB_SPIN(xb_ld(&bar[XB_XGEN(b.x)]) == gen, bar);
.LBB0_731:
	s_or_b64 exec, exec, s[12:13]
	v_cvt_f32_u32_e32 v4, v2
	s_waitcnt vmcnt(1)
	v_readfirstlane_b32 s0, v3
	v_sub_u32_e32 v3, 0, v2
	v_rcp_iflag_f32_e32 v4, v4
	v_add_u32_e32 v5, s0, v1
	v_mul_f32_e32 v4, 0x4f7ffffe, v4
	v_cvt_u32_f32_e32 v4, v4
	v_mul_lo_u32 v1, v3, v4
	v_mul_hi_u32 v1, v4, v1
	v_add_u32_e32 v1, v4, v1
	v_mul_hi_u32 v1, v5, v1
	v_mul_lo_u32 v3, v1, v2
	v_sub_u32_e32 v3, v5, v3
	v_add_u32_e32 v4, 1, v1
	v_cmp_ge_u32_e32 vcc, v3, v2
	s_nop 1
	v_cndmask_b32_e32 v1, v1, v4, vcc
	v_sub_u32_e32 v4, v3, v2
	v_cndmask_b32_e32 v3, v3, v4, vcc
	v_add_u32_e32 v4, 1, v1
	v_cmp_ge_u32_e32 vcc, v3, v2
	v_add_u32_e32 v3, 1, v5
	s_nop 0
	v_cndmask_b32_e32 v1, v1, v4, vcc
	v_mul_lo_u32 v4, v2, v1
	v_add_u32_e32 v2, v4, v2
	v_cmp_ne_u32_e32 vcc, v3, v2
	s_and_saveexec_b64 s[0:1], vcc
	s_xor_b64 s[12:13], exec, s[0:1]
	s_cbranch_execz .LBB0_745
	s_waitcnt lgkmcnt(0)
	global_load_dword v0, v254, s[10:11] offset:1024 sc1
	s_add_u32 s24, s10, 0x2400
	s_addc_u32 s25, s11, 0
	s_waitcnt vmcnt(0)
	v_cmp_eq_u32_e32 vcc, v0, v1
	s_and_saveexec_b64 s[14:15], vcc
	s_cbranch_execz .LBB0_744
	s_mov_b32 s36, 1
	s_mov_b64 s[26:27], 0
	s_branch .LBB0_735

; __device__ __forceinline__ unsigned xb_ld(unsigned* p)              { return __hip_atomic_load(p, __ATOMIC_RELAXED, __HIP_MEMORY_SCOPE_AGENT); }
; __device__ __forceinline__ unsigned xb_add(unsigned* p, unsigned v) { return __hip_atomic_fetch_add(p, v, __ATOMIC_RELAXED, __HIP_MEMORY_SCOPE_AGENT); }
; #define XB_SPIN(cond, bar) do { unsigned _sp = 0; while (cond) { __builtin_amdgcn_s_sleep(1); \
;     if ((++_sp & 255u) == 0u) { if (xb_ld(&(bar)[XB_TMO])) break; if (_sp > XB_SPIN_CAP) { atomicAdd(&(bar)[XB_TMO], 1u); break; } } } } while (0)
; __device__ __forceinline__ void xcd_barrier(const XcdBarrier& b, bool tid0) {
;     ...
;             const unsigned og = xb_add(&bar[XB_TOP], 1u);
;             const unsigned tg = og / nx;
;             if (og + 1u == (tg + 1u) * nx) xb_add(&bar[XB_TOPGEN], 1u);
;             else XB_SPIN(xb_ld(&bar[XB_TOPGEN]) == tg, bar);
;             __builtin_amdgcn_fence(__ATOMIC_ACQUIRE, "agent");
;             xb_add(&bar[XB_XGEN(b.x)], 1u);
;             asm volatile("s_waitcnt vmcnt(0)" ::: "memory");
.LBB0_760:
	s_or_b64 exec, exec, s[14:15]
	s_and_saveexec_b64 s[8:9], s[0:1]
	s_cbranch_execz .LBB0_762
	global_atomic_add v[0:1], v234, off
.LBB0_762:
	s_or_b64 exec, exec, s[8:9]
	s_waitcnt vmcnt(0)
.Lfastbar_6:
	s_mov_b64 s[0:1], exec
	v_mbcnt_lo_u32_b32 v0, s0, 0
	v_mbcnt_hi_u32_b32 v0, s1, v0
	v_cmp_eq_u32_e32 vcc, 0, v0
	s_and_saveexec_b64 s[8:9], vcc
	s_cbranch_execz .LBB0_764
	s_bcnt1_i32_b64 s0, s[0:1]
	v_mov_b32_e32 v0, s0
	global_atomic_add v254, v0, s[10:11] offset:1024

; __device__ __forceinline__ unsigned xb_ld(unsigned* p)              { return __hip_atomic_load(p, __ATOMIC_RELAXED, __HIP_MEMORY_SCOPE_AGENT); }
; __device__ __forceinline__ unsigned xb_add(unsigned* p, unsigned v) { return __hip_atomic_fetch_add(p, v, __ATOMIC_RELAXED, __HIP_MEMORY_SCOPE_AGENT); }
; #define XB_SPIN(cond, bar) do { unsigned _sp = 0; while (cond) { __builtin_amdgcn_s_sleep(1); \
;     if ((++_sp & 255u) == 0u) { if (xb_ld(&(bar)[XB_TMO])) break; if (_sp > XB_SPIN_CAP) { atomicAdd(&(bar)[XB_TMO], 1u); break; } } } } while (0)
; __device__ __forceinline__ void xcd_barrier(const XcdBarrier& b, bool tid0) {
;     ...
;         unsigned nloc = b.st[0], nx = b.st[1];
;         if (nloc == 0u) { xcd_barrier_complete(bar, b.x, b.G, nloc, nx); b.st[0] = nloc; b.st[1] = nx; }
;         const unsigned old = xb_add(&bar[XB_XSUB(b.x)], 1u);
;         const unsigned gen = old / nloc;
;         if (old + 1u == (gen + 1u) * nloc) {
;             __builtin_amdgcn_fence(__ATOMIC_RELEASE, "agent");
;             asm volatile("s_waitcnt vmcnt(0)" ::: "memory");
;             const unsigned og = xb_add(&bar[XB_TOP], 1u);
;             const unsigned tg = og / nx;
;             if (og + 1u == (tg + 1u) * nx) xb_add(&bar[XB_TOPGEN], 1u);
;             else XB_SPIN(xb_ld(&bar[XB_TOPGEN]) == tg, bar);
;             __builtin_amdgcn_fence(__ATOMIC_ACQUIRE, "agent");
;             xb_add(&bar[XB_XGEN(b.x)], 1u);
;             asm volatile("s_waitcnt vmcnt(0)" ::: "memory");
;         } else {
;             XB_SPIN(xb_ld(&bar[XB_XGEN(b.x)]) == gen, bar);
.LBB0_825:
	s_or_b64 exec, exec, s[10:11]
	v_cvt_f32_u32_e32 v4, v2
	s_waitcnt vmcnt(1)
	v_readfirstlane_b32 s0, v3
	v_sub_u32_e32 v3, 0, v2
	v_rcp_iflag_f32_e32 v4, v4
	v_add_u32_e32 v5, s0, v1
	v_mul_f32_e32 v4, 0x4f7ffffe, v4
	v_cvt_u32_f32_e32 v4, v4
	v_mul_lo_u32 v1, v3, v4
	v_mul_hi_u32 v1, v4, v1
	v_add_u32_e32 v1, v4, v1
	v_mul_hi_u32 v1, v5, v1
	v_mul_lo_u32 v3, v1, v2
	v_sub_u32_e32 v3, v5, v3
	v_add_u32_e32 v4, 1, v1
	v_cmp_ge_u32_e32 vcc, v3, v2
	s_nop 1
	v_cndmask_b32_e32 v1, v1, v4, vcc
	v_sub_u32_e32 v4, v3, v2
	v_cndmask_b32_e32 v3, v3, v4, vcc
	v_add_u32_e32 v4, 1, v1
	v_cmp_ge_u32_e32 vcc, v3, v2
	v_add_u32_e32 v3, 1, v5
	s_nop 0
	v_cndmask_b32_e32 v1, v1, v4, vcc
	v_mul_lo_u32 v4, v2, v1
	v_add_u32_e32 v2, v4, v2
	v_cmp_ne_u32_e32 vcc, v3, v2
	s_and_saveexec_b64 s[0:1], vcc
	s_xor_b64 s[10:11], exec, s[0:1]
	s_cbranch_execz .LBB0_839
	s_waitcnt lgkmcnt(0)
	global_load_dword v0, v254, s[8:9] offset:1024 sc1
	s_add_u32 s14, s8, 0x2400
	s_addc_u32 s15, s9, 0
	s_waitcnt vmcnt(0)
	v_cmp_eq_u32_e32 vcc, v0, v1
	s_and_saveexec_b64 s[12:13], vcc
	s_cbranch_execz .LBB0_838
	s_mov_b32 s34, 1
	s_mov_b64 s[24:25], 0
	s_branch .LBB0_829

; __device__ __forceinline__ unsigned xb_ld(unsigned* p)              { return __hip_atomic_load(p, __ATOMIC_RELAXED, __HIP_MEMORY_SCOPE_AGENT); }
; __device__ __forceinline__ unsigned xb_add(unsigned* p, unsigned v) { return __hip_atomic_fetch_add(p, v, __ATOMIC_RELAXED, __HIP_MEMORY_SCOPE_AGENT); }
; #define XB_SPIN(cond, bar) do { unsigned _sp = 0; while (cond) { __builtin_amdgcn_s_sleep(1); \
;     if ((++_sp & 255u) == 0u) { if (xb_ld(&(bar)[XB_TMO])) break; if (_sp > XB_SPIN_CAP) { atomicAdd(&(bar)[XB_TMO], 1u); break; } } } } while (0)
; __device__ __forceinline__ void xcd_barrier(const XcdBarrier& b, bool tid0) {
;     ...
;             const unsigned og = xb_add(&bar[XB_TOP], 1u);
;             const unsigned tg = og / nx;
;             if (og + 1u == (tg + 1u) * nx) xb_add(&bar[XB_TOPGEN], 1u);
;             else XB_SPIN(xb_ld(&bar[XB_TOPGEN]) == tg, bar);
;             __builtin_amdgcn_fence(__ATOMIC_ACQUIRE, "agent");
;             xb_add(&bar[XB_XGEN(b.x)], 1u);
;             asm volatile("s_waitcnt vmcnt(0)" ::: "memory");
.LBB0_854:
	s_or_b64 exec, exec, s[12:13]
	s_and_saveexec_b64 s[6:7], s[0:1]
	s_cbranch_execz .LBB0_856
	global_atomic_add v[0:1], v234, off
.LBB0_856:
	s_or_b64 exec, exec, s[6:7]
	s_waitcnt vmcnt(0)
.Lfastbar_3:
	s_mov_b64 s[0:1], exec
	v_mbcnt_lo_u32_b32 v0, s0, 0
	v_mbcnt_hi_u32_b32 v0, s1, v0
	v_cmp_eq_u32_e32 vcc, 0, v0
	s_and_saveexec_b64 s[6:7], vcc
	s_cbranch_execz .LBB0_858
	s_bcnt1_i32_b64 s0, s[0:1]
	v_mov_b32_e32 v0, s0
	global_atomic_add v254, v0, s[8:9] offset:1024

; __device__ __forceinline__ unsigned xb_ld(unsigned* p)              { return __hip_atomic_load(p, __ATOMIC_RELAXED, __HIP_MEMORY_SCOPE_AGENT); }
; __device__ __forceinline__ unsigned xb_add(unsigned* p, unsigned v) { return __hip_atomic_fetch_add(p, v, __ATOMIC_RELAXED, __HIP_MEMORY_SCOPE_AGENT); }
; #define XB_SPIN(cond, bar) do { unsigned _sp = 0; while (cond) { __builtin_amdgcn_s_sleep(1); \
;     if ((++_sp & 255u) == 0u) { if (xb_ld(&(bar)[XB_TMO])) break; if (_sp > XB_SPIN_CAP) { atomicAdd(&(bar)[XB_TMO], 1u); break; } } } } while (0)
; __device__ __forceinline__ void xcd_barrier(const XcdBarrier& b, bool tid0) {
;     ...
;         unsigned nloc = b.st[0], nx = b.st[1];
;         if (nloc == 0u) { xcd_barrier_complete(bar, b.x, b.G, nloc, nx); b.st[0] = nloc; b.st[1] = nx; }
;         const unsigned old = xb_add(&bar[XB_XSUB(b.x)], 1u);
;         const unsigned gen = old / nloc;
;         if (old + 1u == (gen + 1u) * nloc) {
;             __builtin_amdgcn_fence(__ATOMIC_RELEASE, "agent");
;             asm volatile("s_waitcnt vmcnt(0)" ::: "memory");
;             const unsigned og = xb_add(&bar[XB_TOP], 1u);
;             const unsigned tg = og / nx;
;             if (og + 1u == (tg + 1u) * nx) xb_add(&bar[XB_TOPGEN], 1u);
;             else XB_SPIN(xb_ld(&bar[XB_TOPGEN]) == tg, bar);
;             __builtin_amdgcn_fence(__ATOMIC_ACQUIRE, "agent");
;             xb_add(&bar[XB_XGEN(b.x)], 1u);
;             asm volatile("s_waitcnt vmcnt(0)" ::: "memory");
;         } else {
;             XB_SPIN(xb_ld(&bar[XB_XGEN(b.x)]) == gen, bar);
.LBB0_896:
	s_or_b64 exec, exec, s[8:9]
	v_cvt_f32_u32_e32 v4, v2
	s_waitcnt vmcnt(1)
	v_readfirstlane_b32 s0, v3
	v_sub_u32_e32 v3, 0, v2
	v_rcp_iflag_f32_e32 v4, v4
	v_add_u32_e32 v5, s0, v1
	v_mul_f32_e32 v4, 0x4f7ffffe, v4
	v_cvt_u32_f32_e32 v4, v4
	v_mul_lo_u32 v1, v3, v4
	v_mul_hi_u32 v1, v4, v1
	v_add_u32_e32 v1, v4, v1
	v_mul_hi_u32 v1, v5, v1
	v_mul_lo_u32 v3, v1, v2
	v_sub_u32_e32 v3, v5, v3
	v_add_u32_e32 v4, 1, v1
	v_cmp_ge_u32_e32 vcc, v3, v2
	s_nop 1
	v_cndmask_b32_e32 v1, v1, v4, vcc
	v_sub_u32_e32 v4, v3, v2
	v_cndmask_b32_e32 v3, v3, v4, vcc
	v_add_u32_e32 v4, 1, v1
	v_cmp_ge_u32_e32 vcc, v3, v2
	v_add_u32_e32 v3, 1, v5
	s_nop 0
	v_cndmask_b32_e32 v1, v1, v4, vcc
	v_mul_lo_u32 v4, v2, v1
	v_add_u32_e32 v2, v4, v2
	v_cmp_ne_u32_e32 vcc, v3, v2
	s_and_saveexec_b64 s[0:1], vcc
	s_xor_b64 s[8:9], exec, s[0:1]
	s_cbranch_execz .LBB0_910
	s_waitcnt lgkmcnt(0)
	global_load_dword v0, v254, s[6:7] offset:1024 sc1
	s_add_u32 s12, s6, 0x2400
	s_addc_u32 s13, s7, 0
	s_waitcnt vmcnt(0)
	v_cmp_eq_u32_e32 vcc, v0, v1
	s_and_saveexec_b64 s[10:11], vcc
	s_cbranch_execz .LBB0_909
	s_mov_b32 s22, 1
	s_mov_b64 s[14:15], 0
	s_branch .LBB0_900

; __device__ __forceinline__ unsigned xb_ld(unsigned* p)              { return __hip_atomic_load(p, __ATOMIC_RELAXED, __HIP_MEMORY_SCOPE_AGENT); }
; __device__ __forceinline__ unsigned xb_add(unsigned* p, unsigned v) { return __hip_atomic_fetch_add(p, v, __ATOMIC_RELAXED, __HIP_MEMORY_SCOPE_AGENT); }
; #define XB_SPIN(cond, bar) do { unsigned _sp = 0; while (cond) { __builtin_amdgcn_s_sleep(1); \
;     if ((++_sp & 255u) == 0u) { if (xb_ld(&(bar)[XB_TMO])) break; if (_sp > XB_SPIN_CAP) { atomicAdd(&(bar)[XB_TMO], 1u); break; } } } } while (0)
; __device__ __forceinline__ void xcd_barrier(const XcdBarrier& b, bool tid0) {
;     ...
;             const unsigned og = xb_add(&bar[XB_TOP], 1u);
;             const unsigned tg = og / nx;
;             if (og + 1u == (tg + 1u) * nx) xb_add(&bar[XB_TOPGEN], 1u);
;             else XB_SPIN(xb_ld(&bar[XB_TOPGEN]) == tg, bar);
;             __builtin_amdgcn_fence(__ATOMIC_ACQUIRE, "agent");
;             xb_add(&bar[XB_XGEN(b.x)], 1u);
;             asm volatile("s_waitcnt vmcnt(0)" ::: "memory");
.LBB0_925:
	s_or_b64 exec, exec, s[10:11]
	s_and_saveexec_b64 s[4:5], s[0:1]
	s_cbranch_execz .LBB0_927
	global_atomic_add v[0:1], v234, off
.LBB0_927:
	s_or_b64 exec, exec, s[4:5]
	s_waitcnt vmcnt(0)

; __device__ __forceinline__ unsigned xb_ld(unsigned* p)              { return __hip_atomic_load(p, __ATOMIC_RELAXED, __HIP_MEMORY_SCOPE_AGENT); }
; __device__ __forceinline__ unsigned xb_add(unsigned* p, unsigned v) { return __hip_atomic_fetch_add(p, v, __ATOMIC_RELAXED, __HIP_MEMORY_SCOPE_AGENT); }
; #define XB_SPIN(cond, bar) do { unsigned _sp = 0; while (cond) { __builtin_amdgcn_s_sleep(1); \
;     if ((++_sp & 255u) == 0u) { if (xb_ld(&(bar)[XB_TMO])) break; if (_sp > XB_SPIN_CAP) { atomicAdd(&(bar)[XB_TMO], 1u); break; } } } } while (0)
; __device__ __forceinline__ void xcd_barrier(const XcdBarrier& b, bool tid0) {
;     ...
;         unsigned nloc = b.st[0], nx = b.st[1];
;         if (nloc == 0u) { xcd_barrier_complete(bar, b.x, b.G, nloc, nx); b.st[0] = nloc; b.st[1] = nx; }
;         const unsigned old = xb_add(&bar[XB_XSUB(b.x)], 1u);
;         const unsigned gen = old / nloc;
;         if (old + 1u == (gen + 1u) * nloc) {
;             __builtin_amdgcn_fence(__ATOMIC_RELEASE, "agent");
;             asm volatile("s_waitcnt vmcnt(0)" ::: "memory");
;             const unsigned og = xb_add(&bar[XB_TOP], 1u);
;             const unsigned tg = og / nx;
;             if (og + 1u == (tg + 1u) * nx) xb_add(&bar[XB_TOPGEN], 1u);
;             else XB_SPIN(xb_ld(&bar[XB_TOPGEN]) == tg, bar);
;             __builtin_amdgcn_fence(__ATOMIC_ACQUIRE, "agent");
;             xb_add(&bar[XB_XGEN(b.x)], 1u);
;             asm volatile("s_waitcnt vmcnt(0)" ::: "memory");
;         } else {
;             XB_SPIN(xb_ld(&bar[XB_XGEN(b.x)]) == gen, bar);
.LBB0_949:
	s_or_b64 exec, exec, s[8:9]
	v_cvt_f32_u32_e32 v4, v2
	s_waitcnt vmcnt(1)
	v_readfirstlane_b32 s0, v3
	v_sub_u32_e32 v3, 0, v2
	v_rcp_iflag_f32_e32 v4, v4
	v_add_u32_e32 v5, s0, v1
	v_mul_f32_e32 v4, 0x4f7ffffe, v4
	v_cvt_u32_f32_e32 v4, v4
	v_mul_lo_u32 v1, v3, v4
	v_mul_hi_u32 v1, v4, v1
	v_add_u32_e32 v1, v4, v1
	v_mul_hi_u32 v1, v5, v1
	v_mul_lo_u32 v3, v1, v2
	v_sub_u32_e32 v3, v5, v3
	v_add_u32_e32 v4, 1, v1
	v_cmp_ge_u32_e32 vcc, v3, v2
	s_nop 1
	v_cndmask_b32_e32 v1, v1, v4, vcc
	v_sub_u32_e32 v4, v3, v2
	v_cndmask_b32_e32 v3, v3, v4, vcc
	v_add_u32_e32 v4, 1, v1
	v_cmp_ge_u32_e32 vcc, v3, v2
	v_add_u32_e32 v3, 1, v5
	s_nop 0
	v_cndmask_b32_e32 v1, v1, v4, vcc
	v_mul_lo_u32 v4, v2, v1
	v_add_u32_e32 v2, v4, v2
	v_cmp_ne_u32_e32 vcc, v3, v2
	s_and_saveexec_b64 s[0:1], vcc
	s_xor_b64 s[8:9], exec, s[0:1]
	s_cbranch_execz .LBB0_963
	s_waitcnt lgkmcnt(0)
	global_load_dword v0, v254, s[6:7] offset:1024 sc1
	s_add_u32 s14, s6, 0x2400
	s_addc_u32 s15, s7, 0
	s_waitcnt vmcnt(0)
	v_cmp_eq_u32_e32 vcc, v0, v1
	s_and_saveexec_b64 s[10:11], vcc
	s_cbranch_execz .LBB0_962
	s_add_u32 s12, s4, 0x26120200
	s_addc_u32 s13, s5, 0
	s_mov_b32 s24, 1
	s_mov_b64 s[16:17], 0
	s_branch .LBB0_953

; __device__ __forceinline__ unsigned xb_ld(unsigned* p)              { return __hip_atomic_load(p, __ATOMIC_RELAXED, __HIP_MEMORY_SCOPE_AGENT); }
; __device__ __forceinline__ unsigned xb_add(unsigned* p, unsigned v) { return __hip_atomic_fetch_add(p, v, __ATOMIC_RELAXED, __HIP_MEMORY_SCOPE_AGENT); }
; #define XB_SPIN(cond, bar) do { unsigned _sp = 0; while (cond) { __builtin_amdgcn_s_sleep(1); \
;     if ((++_sp & 255u) == 0u) { if (xb_ld(&(bar)[XB_TMO])) break; if (_sp > XB_SPIN_CAP) { atomicAdd(&(bar)[XB_TMO], 1u); break; } } } } while (0)
; __device__ __forceinline__ void xcd_barrier(const XcdBarrier& b, bool tid0) {
;     ...
;         unsigned nloc = b.st[0], nx = b.st[1];
;         if (nloc == 0u) { xcd_barrier_complete(bar, b.x, b.G, nloc, nx); b.st[0] = nloc; b.st[1] = nx; }
;         const unsigned old = xb_add(&bar[XB_XSUB(b.x)], 1u);
;         const unsigned gen = old / nloc;
;         if (old + 1u == (gen + 1u) * nloc) {
;             __builtin_amdgcn_fence(__ATOMIC_RELEASE, "agent");
;             asm volatile("s_waitcnt vmcnt(0)" ::: "memory");
;             const unsigned og = xb_add(&bar[XB_TOP], 1u);
;             const unsigned tg = og / nx;
;             if (og + 1u == (tg + 1u) * nx) xb_add(&bar[XB_TOPGEN], 1u);
;             else XB_SPIN(xb_ld(&bar[XB_TOPGEN]) == tg, bar);
;             __builtin_amdgcn_fence(__ATOMIC_ACQUIRE, "agent");
;             xb_add(&bar[XB_XGEN(b.x)], 1u);
;             asm volatile("s_waitcnt vmcnt(0)" ::: "memory");
;         } else {
;             XB_SPIN(xb_ld(&bar[XB_XGEN(b.x)]) == gen, bar);
.LBB0_1016:
	s_or_b64 exec, exec, s[0:1]
	v_cvt_f32_u32_e32 v4, v2
	s_waitcnt vmcnt(1)
	v_readfirstlane_b32 s0, v3
	v_sub_u32_e32 v3, 0, v2
	v_rcp_iflag_f32_e32 v4, v4
	v_add_u32_e32 v5, s0, v1
	v_mul_f32_e32 v4, 0x4f7ffffe, v4
	v_cvt_u32_f32_e32 v4, v4
	v_mul_lo_u32 v1, v3, v4
	v_mul_hi_u32 v1, v4, v1
	v_add_u32_e32 v1, v4, v1
	v_mul_hi_u32 v1, v5, v1
	v_mul_lo_u32 v3, v1, v2
	v_sub_u32_e32 v3, v5, v3
	v_add_u32_e32 v4, 1, v1
	v_cmp_ge_u32_e32 vcc, v3, v2
	s_nop 1
	v_cndmask_b32_e32 v1, v1, v4, vcc
	v_sub_u32_e32 v4, v3, v2
	v_cndmask_b32_e32 v3, v3, v4, vcc
	v_add_u32_e32 v4, 1, v1
	v_cmp_ge_u32_e32 vcc, v3, v2
	v_add_u32_e32 v3, 1, v5
	s_nop 0
	v_cndmask_b32_e32 v1, v1, v4, vcc
	v_mul_lo_u32 v4, v2, v1
	v_add_u32_e32 v2, v4, v2
	v_cmp_ne_u32_e32 vcc, v3, v2
	s_and_saveexec_b64 s[0:1], vcc
	s_xor_b64 s[64:65], exec, s[0:1]
	s_cbranch_execz .LBB0_1030
	s_waitcnt lgkmcnt(0)
	global_load_dword v0, v177, s[52:53] sc1
	s_waitcnt vmcnt(0)
	v_cmp_eq_u32_e32 vcc, v0, v1
	s_and_saveexec_b64 s[42:43], vcc
	s_cbranch_execz .LBB0_1029
	s_mov_b32 s24, 1
	s_mov_b64 s[4:5], 0
	s_branch .LBB0_1020

; __device__ __forceinline__ unsigned xb_ld(unsigned* p)              { return __hip_atomic_load(p, __ATOMIC_RELAXED, __HIP_MEMORY_SCOPE_AGENT); }
; __device__ __forceinline__ unsigned xb_add(unsigned* p, unsigned v) { return __hip_atomic_fetch_add(p, v, __ATOMIC_RELAXED, __HIP_MEMORY_SCOPE_AGENT); }
; #define XB_SPIN(cond, bar) do { unsigned _sp = 0; while (cond) { __builtin_amdgcn_s_sleep(1); \
;     if ((++_sp & 255u) == 0u) { if (xb_ld(&(bar)[XB_TMO])) break; if (_sp > XB_SPIN_CAP) { atomicAdd(&(bar)[XB_TMO], 1u); break; } } } } while (0)
; __device__ __forceinline__ void xcd_barrier(const XcdBarrier& b, bool tid0) {
;     ...
;             const unsigned og = xb_add(&bar[XB_TOP], 1u);
;             const unsigned tg = og / nx;
;             if (og + 1u == (tg + 1u) * nx) xb_add(&bar[XB_TOPGEN], 1u);
;             else XB_SPIN(xb_ld(&bar[XB_TOPGEN]) == tg, bar);
;             __builtin_amdgcn_fence(__ATOMIC_ACQUIRE, "agent");
;             xb_add(&bar[XB_XGEN(b.x)], 1u);
;             asm volatile("s_waitcnt vmcnt(0)" ::: "memory");
.LBB0_1045:
	s_or_b64 exec, exec, s[42:43]
	s_and_saveexec_b64 s[4:5], s[0:1]
	s_cbranch_execz .LBB0_1047
	global_atomic_add v[0:1], v234, off
.LBB0_1047:
	s_or_b64 exec, exec, s[4:5]
	s_waitcnt vmcnt(0)
.Lfastbar_5:
	s_mov_b64 s[0:1], exec
	v_mbcnt_lo_u32_b32 v0, s0, 0
	v_mbcnt_hi_u32_b32 v0, s1, v0
	v_cmp_eq_u32_e32 vcc, 0, v0
	s_and_saveexec_b64 s[4:5], vcc
	s_cbranch_execz .LBB0_1049
	s_bcnt1_i32_b64 s0, s[0:1]
	v_mov_b32_e32 v0, s0
	global_atomic_add v177, v0, s[52:53]
